# software-pipelined RMSNorm row loops (params batched, next-row prefetch) + counted vmcnt in kv_chunk head loops + unrolled silu(c) prologue loads
# speedup vs baseline: 1.0110x; 1.0110x over previous
; DI float fsilu(float x) { return x * fsigmoid(x); }
; DI void phase_mod(CP p, LAS unsigned char* lds) {
;     ...
;     for (int i = tid; i < 8192; i += 512) ca[i] = fsilu(p->c[i]);
.LBB0_7:
	global_load_dword v10, v[4:5], off
	v_lshl_add_u64 v[4:5], v[4:5], 0, s[16:17]
	global_load_dword v11, v[4:5], off
	v_lshl_add_u64 v[4:5], v[4:5], 0, s[16:17]
	global_load_dword v12, v[4:5], off
	v_lshl_add_u64 v[4:5], v[4:5], 0, s[16:17]
	global_load_dword v13, v[4:5], off
	v_lshl_add_u64 v[4:5], v[4:5], 0, s[16:17]
	global_load_dword v14, v[4:5], off
	v_lshl_add_u64 v[4:5], v[4:5], 0, s[16:17]
	global_load_dword v15, v[4:5], off
	v_lshl_add_u64 v[4:5], v[4:5], 0, s[16:17]
	global_load_dword v16, v[4:5], off
	v_lshl_add_u64 v[4:5], v[4:5], 0, s[16:17]
	global_load_dword v17, v[4:5], off
	v_lshl_add_u64 v[4:5], v[4:5], 0, s[16:17]
	global_load_dword v18, v[4:5], off
	v_lshl_add_u64 v[4:5], v[4:5], 0, s[16:17]
	global_load_dword v19, v[4:5], off
	v_lshl_add_u64 v[4:5], v[4:5], 0, s[16:17]
	global_load_dword v20, v[4:5], off
	v_lshl_add_u64 v[4:5], v[4:5], 0, s[16:17]
	global_load_dword v21, v[4:5], off
	v_lshl_add_u64 v[4:5], v[4:5], 0, s[16:17]
	global_load_dword v22, v[4:5], off
	v_lshl_add_u64 v[4:5], v[4:5], 0, s[16:17]
	global_load_dword v23, v[4:5], off
	v_lshl_add_u64 v[4:5], v[4:5], 0, s[16:17]
	global_load_dword v24, v[4:5], off
	v_lshl_add_u64 v[4:5], v[4:5], 0, s[16:17]
	global_load_dword v25, v[4:5], off
	v_lshl_add_u64 v[4:5], v[4:5], 0, s[16:17]
	s_waitcnt vmcnt(15)
	v_mul_f32_e32 v7, 0xbfb8aa3b, v10
	v_exp_f32_e32 v7, v7
	s_nop 0
	v_add_f32_e32 v7, 1.0, v7
	v_rcp_f32_e32 v7, v7
	s_nop 0
	v_mul_f32_e32 v3, v10, v7
	ds_write_b32 v6, v3
	s_waitcnt vmcnt(14)
	v_mul_f32_e32 v7, 0xbfb8aa3b, v11
	v_exp_f32_e32 v7, v7
	s_nop 0
	v_add_f32_e32 v7, 1.0, v7
	v_rcp_f32_e32 v7, v7
	s_nop 0
	v_mul_f32_e32 v3, v11, v7
	ds_write_b32 v6, v3 offset:2048
	s_waitcnt vmcnt(13)
	v_mul_f32_e32 v7, 0xbfb8aa3b, v12
	v_exp_f32_e32 v7, v7
	s_nop 0
	v_add_f32_e32 v7, 1.0, v7
	v_rcp_f32_e32 v7, v7
	s_nop 0
	v_mul_f32_e32 v3, v12, v7
	ds_write_b32 v6, v3 offset:4096
	s_waitcnt vmcnt(12)
	v_mul_f32_e32 v7, 0xbfb8aa3b, v13
	v_exp_f32_e32 v7, v7
	s_nop 0
	v_add_f32_e32 v7, 1.0, v7
	v_rcp_f32_e32 v7, v7
	s_nop 0
	v_mul_f32_e32 v3, v13, v7
	ds_write_b32 v6, v3 offset:6144
	s_waitcnt vmcnt(11)
	v_mul_f32_e32 v7, 0xbfb8aa3b, v14
	v_exp_f32_e32 v7, v7
	s_nop 0
	v_add_f32_e32 v7, 1.0, v7
	v_rcp_f32_e32 v7, v7
	s_nop 0
	v_mul_f32_e32 v3, v14, v7
	ds_write_b32 v6, v3 offset:8192
	s_waitcnt vmcnt(10)
	v_mul_f32_e32 v7, 0xbfb8aa3b, v15
	v_exp_f32_e32 v7, v7
	s_nop 0
	v_add_f32_e32 v7, 1.0, v7
	v_rcp_f32_e32 v7, v7
	s_nop 0
	v_mul_f32_e32 v3, v15, v7
	ds_write_b32 v6, v3 offset:10240
	s_waitcnt vmcnt(9)
	v_mul_f32_e32 v7, 0xbfb8aa3b, v16
	v_exp_f32_e32 v7, v7
	s_nop 0
	v_add_f32_e32 v7, 1.0, v7
	v_rcp_f32_e32 v7, v7
	s_nop 0
	v_mul_f32_e32 v3, v16, v7
	ds_write_b32 v6, v3 offset:12288
	s_waitcnt vmcnt(8)
	v_mul_f32_e32 v7, 0xbfb8aa3b, v17
	v_exp_f32_e32 v7, v7
	s_nop 0
	v_add_f32_e32 v7, 1.0, v7
	v_rcp_f32_e32 v7, v7
	s_nop 0
	v_mul_f32_e32 v3, v17, v7
	ds_write_b32 v6, v3 offset:14336
	s_waitcnt vmcnt(7)
	v_mul_f32_e32 v7, 0xbfb8aa3b, v18
	v_exp_f32_e32 v7, v7
	s_nop 0
	v_add_f32_e32 v7, 1.0, v7
	v_rcp_f32_e32 v7, v7
	s_nop 0
	v_mul_f32_e32 v3, v18, v7
	ds_write_b32 v6, v3 offset:16384
	s_waitcnt vmcnt(6)
	v_mul_f32_e32 v7, 0xbfb8aa3b, v19
	v_exp_f32_e32 v7, v7
	s_nop 0
	v_add_f32_e32 v7, 1.0, v7
	v_rcp_f32_e32 v7, v7
	s_nop 0
	v_mul_f32_e32 v3, v19, v7
	ds_write_b32 v6, v3 offset:18432
	s_waitcnt vmcnt(5)
	v_mul_f32_e32 v7, 0xbfb8aa3b, v20
	v_exp_f32_e32 v7, v7
	s_nop 0
	v_add_f32_e32 v7, 1.0, v7
	v_rcp_f32_e32 v7, v7
	s_nop 0
	v_mul_f32_e32 v3, v20, v7
	ds_write_b32 v6, v3 offset:20480
	s_waitcnt vmcnt(4)
	v_mul_f32_e32 v7, 0xbfb8aa3b, v21
	v_exp_f32_e32 v7, v7
	s_nop 0
	v_add_f32_e32 v7, 1.0, v7
	v_rcp_f32_e32 v7, v7
	s_nop 0
	v_mul_f32_e32 v3, v21, v7
	ds_write_b32 v6, v3 offset:22528
	s_waitcnt vmcnt(3)
	v_mul_f32_e32 v7, 0xbfb8aa3b, v22
	v_exp_f32_e32 v7, v7
	s_nop 0
	v_add_f32_e32 v7, 1.0, v7
	v_rcp_f32_e32 v7, v7
	s_nop 0
	v_mul_f32_e32 v3, v22, v7
	ds_write_b32 v6, v3 offset:24576
	s_waitcnt vmcnt(2)
	v_mul_f32_e32 v7, 0xbfb8aa3b, v23
	v_exp_f32_e32 v7, v7
	s_nop 0
	v_add_f32_e32 v7, 1.0, v7
	v_rcp_f32_e32 v7, v7
	s_nop 0
	v_mul_f32_e32 v3, v23, v7
	ds_write_b32 v6, v3 offset:26624
	s_waitcnt vmcnt(1)
	v_mul_f32_e32 v7, 0xbfb8aa3b, v24
	v_exp_f32_e32 v7, v7
	s_nop 0
	v_add_f32_e32 v7, 1.0, v7
	v_rcp_f32_e32 v7, v7
	s_nop 0
	v_mul_f32_e32 v3, v24, v7
	ds_write_b32 v6, v3 offset:28672
	s_waitcnt vmcnt(0)
	v_mul_f32_e32 v7, 0xbfb8aa3b, v25
	v_exp_f32_e32 v7, v7
	s_nop 0
	v_add_f32_e32 v7, 1.0, v7
	v_rcp_f32_e32 v7, v7
	s_nop 0
	v_mul_f32_e32 v3, v25, v7
	ds_write_b32 v6, v3 offset:30720

; DI int fresh_tid() { int t = threadIdx.x; asm volatile("" : "+v"(t)); return t; }
; DI unsigned pk2(float lo, float hi) { f32x2_t v = {lo, hi}; bf16x2_t b = __builtin_convertvector(v, bf16x2_t); return __builtin_bit_cast(unsigned, b); }
; DI void phase_norm(const float* xin, const float* g, const float* shift, const float* scale, bf16* hout) {
;     const int tid = fresh_tid(), lane = tid & 63, wave = tid >> 6;
;     const int gw = blockIdx.x * 8 + wave, NGW = gridDim.x * 8;
;     for (int row = gw; row < T; row += NGW) {
;         const int b = row >> 11;
;         const f32x4* xr = (const f32x4*)(xin + (size_t)row * DM) + lane;
;         f32x4 v[4]; float ss = 0.f;
; #pragma unroll
;         for (int j = 0; j < 4; ++j) { v[j] = xr[64 * j]; ss += (v[j].x * v[j].x + v[j].y * v[j].y) + (v[j].z * v[j].z + v[j].w * v[j].w); }
;         const float r = rsqrtf(wave_sum(ss, lane) * (1.f / DM) + EPS);
; #pragma unroll
;         for (int j = 0; j < 4; ++j) { const int col = 4 * lane + 256 * j;
;             const f32x4 gg = *(const f32x4*)(g + col), sc = *(const f32x4*)(scale + b * 6144 + col), sh = *(const f32x4*)(shift + b * 6144 + col);
;             const f32x4 y = (v[j] * r) * gg * (sc + 1.f) + sh;
;             u32x2 w; w.x = pk2(y.x, y.y); w.y = pk2(y.z, y.w);
;             *(u32x2*)(hout + (size_t)row * DM + col) = w; }
;     }
; }
.LBB0_65:
	global_load_dwordx4 v[76:79], v[10:11], off offset:-3072
	global_load_dwordx4 v[80:83], v[10:11], off offset:-2048
	global_load_dwordx4 v[84:87], v[10:11], off offset:-1024
	global_load_dwordx4 v[88:91], v[10:11], off
	s_waitcnt vmcnt(0)
	s_branch .Lnorm_a_body
.Lnorm_a_loop:
	s_waitcnt vmcnt(4)
.Lnorm_a_body:
	v_mov_b32_e32 v60, v76
	v_mov_b32_e32 v61, v77
	v_mov_b32_e32 v62, v78
	v_mov_b32_e32 v63, v79
	v_mov_b32_e32 v64, v80
	v_mov_b32_e32 v65, v81
	v_mov_b32_e32 v66, v82
	v_mov_b32_e32 v67, v83
	v_mov_b32_e32 v68, v84
	v_mov_b32_e32 v69, v85
	v_mov_b32_e32 v70, v86
	v_mov_b32_e32 v71, v87
	v_mov_b32_e32 v72, v88
	v_mov_b32_e32 v73, v89
	v_mov_b32_e32 v74, v90
	v_mov_b32_e32 v75, v91
	v_ashrrev_i32_e32 v140, 11, v0
	v_mul_i32_i24_e32 v140, 0x1800, v140
	v_ashrrev_i32_e32 v141, 31, v140
	v_lshlrev_b64 v[140:141], 2, v[140:141]
	v_lshl_add_u64 v[150:151], v[4:5], 0, v[140:141]
	v_lshl_add_u64 v[152:153], v[6:7], 0, v[140:141]
	global_load_dwordx4 v[92:95], v[2:3], off
	global_load_dwordx4 v[96:99], v[2:3], off offset:1024
	global_load_dwordx4 v[100:103], v[2:3], off offset:2048
	global_load_dwordx4 v[104:107], v[2:3], off offset:3072
	global_load_dwordx4 v[108:111], v[150:151], off
	global_load_dwordx4 v[112:115], v[150:151], off offset:1024
	global_load_dwordx4 v[116:119], v[150:151], off offset:2048
	global_load_dwordx4 v[120:123], v[150:151], off offset:3072
	global_load_dwordx4 v[124:127], v[152:153], off
	global_load_dwordx4 v[128:131], v[152:153], off offset:1024
	global_load_dwordx4 v[132:135], v[152:153], off offset:2048
	global_load_dwordx4 v[136:139], v[152:153], off offset:3072
	v_add_u32_e32 v146, s84, v0
	v_lshl_add_u64 v[148:149], v[10:11], 0, s[14:15]
	v_cmp_lt_i32_e32 vcc, s56, v146
	s_nop 1
	v_cndmask_b32_e32 v148, v148, v10, vcc
	v_cndmask_b32_e32 v149, v149, v11, vcc
	global_load_dwordx4 v[76:79], v[148:149], off offset:-3072
	global_load_dwordx4 v[80:83], v[148:149], off offset:-2048
	global_load_dwordx4 v[84:87], v[148:149], off offset:-1024
	global_load_dwordx4 v[88:91], v[148:149], off
	v_mul_f32_e32 v154, v60, v60
	v_fmac_f32_e32 v154, v61, v61
	v_mul_f32_e32 v155, v62, v62
	v_fmac_f32_e32 v155, v63, v63
	v_add_f32_e32 v154, v154, v155
	v_mov_b32_e32 v142, v154
	v_mul_f32_e32 v154, v64, v64
	v_fmac_f32_e32 v154, v65, v65
	v_mul_f32_e32 v155, v66, v66
	v_fmac_f32_e32 v155, v67, v67
	v_add_f32_e32 v154, v154, v155
	v_add_f32_e32 v142, v142, v154
	v_mul_f32_e32 v154, v68, v68
	v_fmac_f32_e32 v154, v69, v69
	v_mul_f32_e32 v155, v70, v70
	v_fmac_f32_e32 v155, v71, v71
	v_add_f32_e32 v154, v154, v155
	v_add_f32_e32 v142, v142, v154
	v_mul_f32_e32 v154, v72, v72
	v_fmac_f32_e32 v154, v73, v73
	v_mul_f32_e32 v155, v74, v74
	v_fmac_f32_e32 v155, v75, v75
	v_add_f32_e32 v154, v154, v155
	v_add_f32_e32 v142, v142, v154
	ds_bpermute_b32 v154, v12, v142
	s_waitcnt lgkmcnt(0)
	v_add_f32_e32 v142, v142, v154
	ds_bpermute_b32 v154, v13, v142
	s_waitcnt lgkmcnt(0)
	v_add_f32_e32 v142, v142, v154
	ds_bpermute_b32 v154, v14, v142
	s_waitcnt lgkmcnt(0)
	v_add_f32_e32 v142, v142, v154
	ds_bpermute_b32 v154, v15, v142
	s_waitcnt lgkmcnt(0)
	v_add_f32_e32 v142, v142, v154
	ds_bpermute_b32 v154, v16, v142
	s_waitcnt lgkmcnt(0)
	v_add_f32_e32 v142, v142, v154
	ds_bpermute_b32 v154, v17, v142
	s_waitcnt lgkmcnt(0)
	v_add_f32_e32 v142, v142, v154
	v_fmamk_f32 v142, v142, 0x3a800000, v198
	v_mul_f32_e32 v154, 0x4b800000, v142
	v_cmp_gt_f32_e32 vcc, s67, v142
	s_nop 1
	v_cndmask_b32_e32 v142, v142, v154, vcc
	v_rsq_f32_e32 v142, v142
	s_nop 0
	v_mul_f32_e32 v154, 0x45800000, v142
	v_cndmask_b32_e32 v144, v142, v154, vcc
	s_waitcnt vmcnt(4)
	v_pk_mul_f32 v[60:61], v[60:61], v[144:145] op_sel_hi:[1,0]
	v_pk_mul_f32 v[62:63], v[62:63], v[144:145] op_sel_hi:[1,0]
	v_pk_mul_f32 v[60:61], v[92:93], v[60:61]
	v_pk_mul_f32 v[62:63], v[94:95], v[62:63]
	v_pk_add_f32 v[108:109], v[108:109], 1.0 op_sel_hi:[1,0]
	v_pk_add_f32 v[110:111], v[110:111], 1.0 op_sel_hi:[1,0]
	v_pk_fma_f32 v[60:61], v[108:109], v[60:61], v[124:125]
	v_pk_fma_f32 v[62:63], v[110:111], v[62:63], v[126:127]
	v_cvt_pk_bf16_f32 v60, v60, v61
	v_cvt_pk_bf16_f32 v61, v62, v63
	global_store_dwordx2 v[8:9], v[60:61], off
	v_pk_mul_f32 v[64:65], v[64:65], v[144:145] op_sel_hi:[1,0]
	v_pk_mul_f32 v[66:67], v[66:67], v[144:145] op_sel_hi:[1,0]
	v_pk_mul_f32 v[64:65], v[96:97], v[64:65]
	v_pk_mul_f32 v[66:67], v[98:99], v[66:67]
	v_pk_add_f32 v[112:113], v[112:113], 1.0 op_sel_hi:[1,0]
	v_pk_add_f32 v[114:115], v[114:115], 1.0 op_sel_hi:[1,0]
	v_pk_fma_f32 v[64:65], v[112:113], v[64:65], v[128:129]
	v_pk_fma_f32 v[66:67], v[114:115], v[66:67], v[130:131]
	v_cvt_pk_bf16_f32 v64, v64, v65
	v_cvt_pk_bf16_f32 v65, v66, v67
	global_store_dwordx2 v[8:9], v[64:65], off offset:512
	v_pk_mul_f32 v[68:69], v[68:69], v[144:145] op_sel_hi:[1,0]
	v_pk_mul_f32 v[70:71], v[70:71], v[144:145] op_sel_hi:[1,0]
	v_pk_mul_f32 v[68:69], v[100:101], v[68:69]
	v_pk_mul_f32 v[70:71], v[102:103], v[70:71]
	v_pk_add_f32 v[116:117], v[116:117], 1.0 op_sel_hi:[1,0]
	v_pk_add_f32 v[118:119], v[118:119], 1.0 op_sel_hi:[1,0]
	v_pk_fma_f32 v[68:69], v[116:117], v[68:69], v[132:133]
	v_pk_fma_f32 v[70:71], v[118:119], v[70:71], v[134:135]
	v_cvt_pk_bf16_f32 v68, v68, v69
	v_cvt_pk_bf16_f32 v69, v70, v71
	global_store_dwordx2 v[8:9], v[68:69], off offset:1024
	v_pk_mul_f32 v[72:73], v[72:73], v[144:145] op_sel_hi:[1,0]
	v_pk_mul_f32 v[74:75], v[74:75], v[144:145] op_sel_hi:[1,0]
	v_pk_mul_f32 v[72:73], v[104:105], v[72:73]
	v_pk_mul_f32 v[74:75], v[106:107], v[74:75]
	v_pk_add_f32 v[120:121], v[120:121], 1.0 op_sel_hi:[1,0]
	v_pk_add_f32 v[122:123], v[122:123], 1.0 op_sel_hi:[1,0]
	v_pk_fma_f32 v[72:73], v[120:121], v[72:73], v[136:137]
	v_pk_fma_f32 v[74:75], v[122:123], v[74:75], v[138:139]
	v_cvt_pk_bf16_f32 v72, v72, v73
	v_cvt_pk_bf16_f32 v73, v74, v75
	global_store_dwordx2 v[8:9], v[72:73], off offset:1536
	v_mov_b32_e32 v0, v146
	v_lshl_add_u64 v[10:11], v[10:11], 0, s[14:15]
	v_cmp_lt_i32_e32 vcc, s56, v0
	s_or_b64 s[2:3], vcc, s[2:3]
	v_lshl_add_u64 v[8:9], v[8:9], 0, s[50:51]
	s_andn2_b64 exec, exec, s[2:3]
	s_cbranch_execnz .Lnorm_a_loop

; #define LAS __attribute__((address_space(3)))
; DI unsigned pk2(float lo, float hi) { f32x2_t v = {lo, hi}; bf16x2_t b = __builtin_convertvector(v, bf16x2_t); return __builtin_bit_cast(unsigned, b); }
; DI void unpack8(const u32x4 w, float (&f)[8]) { f[0] = bflo(w.x); f[1] = bfhi(w.x); f[2] = bflo(w.y); f[3] = bfhi(w.y); f[4] = bflo(w.z); f[5] = bfhi(w.z); f[6] = bflo(w.w); f[7] = bfhi(w.w); }
; DI float fexp2(float x) { return __builtin_amdgcn_exp2f(x); }
; DI void kv_chunk(CP p, int b, int n, LAS unsigned char* lds) {
;     ...
;         for (int h = 0; h < 4; ++h) {
;             const float w = fexp2((float)(63 - kj) * log2gamma(h));
;             *(LAS u32x4*)(lds + VT + (tid >> 4) * 272 + (tid & 15) * 16) = rv0; *(LAS u32x4*)(lds + VT + (32 + (tid >> 4)) * 272 + (tid & 15) * 16) = rv1;
;             { float x[8]; unpack8(rk0, x);
; #pragma unroll
;               for (int e = 0; e < 8; ++e) *(LAS bf16*)(lds + KT + (kpt * 8 + e) * 144 + kj * 2) = (bf16)(pk2(x[e] * w, 0.f) & 0xffffu);
;               unpack8(rk1, x);
; #pragma unroll
;               for (int e = 0; e < 8; ++e) *(LAS bf16*)(lds + KT + ((kpt + 8) * 8 + e) * 144 + kj * 2) = (bf16)(pk2(x[e] * w, 0.f) & 0xffffu); }
.LBB0_303:
	v_mul_f32_e32 v38, v38, v19
	v_exp_f32_e32 v38, v38
	s_cmp_lt_i32 s57, 1
	s_cbranch_scc1 .Lkvw_r1_a
	s_waitcnt vmcnt(9)
	s_branch .Lkvw_r1_b
.Lkvw_r1_a:
	s_waitcnt vmcnt(1)
.Lkvw_r1_b:
	v_lshlrev_b32_e32 v39, 16, v8
	v_and_b32_e32 v40, 0xffff0000, v8
	v_add_u32_e32 v49, v21, v33
	v_mul_f32_e32 v39, v38, v39
	v_cvt_pk_bf16_f32 v39, v39, s0
	ds_write_b128 v48, v[0:3]
	ds_write_b128 v48, v[4:7] offset:8704
	ds_write_b16 v49, v39 offset:18432
	v_mul_f32_e32 v39, v38, v40
	v_lshlrev_b32_e32 v41, 16, v9
	v_cvt_pk_bf16_f32 v39, v39, s0
	ds_write_b16 v49, v39 offset:18576
	v_mul_f32_e32 v39, v38, v41
	v_and_b32_e32 v42, 0xffff0000, v9
	v_cvt_pk_bf16_f32 v39, v39, s0
	ds_write_b16 v49, v39 offset:18720
	v_mul_f32_e32 v39, v38, v42
	v_lshlrev_b32_e32 v43, 16, v10
	v_cvt_pk_bf16_f32 v39, v39, s0
	ds_write_b16 v49, v39 offset:18864
	v_mul_f32_e32 v39, v38, v43
	v_and_b32_e32 v45, 0xffff0000, v10
	v_cvt_pk_bf16_f32 v39, v39, s0
	ds_write_b16 v49, v39 offset:19008
	v_mul_f32_e32 v39, v38, v45
	v_lshlrev_b32_e32 v46, 16, v11
	v_cvt_pk_bf16_f32 v39, v39, s0
	ds_write_b16 v49, v39 offset:19152
	v_mul_f32_e32 v39, v38, v46
	v_and_b32_e32 v51, 0xffff0000, v11
	v_cvt_pk_bf16_f32 v39, v39, s0
	ds_write_b16 v49, v39 offset:19296
	v_mul_f32_e32 v39, v38, v51
	v_cvt_pk_bf16_f32 v39, v39, s0
	ds_write_b16 v49, v39 offset:19440
	s_cmp_lt_i32 s57, 1
	s_cbranch_scc1 .Lkvw_r2_a
	s_waitcnt vmcnt(8)
	s_branch .Lkvw_r2_b

; #define LAS __attribute__((address_space(3)))
; DI unsigned pk2(float lo, float hi) { f32x2_t v = {lo, hi}; bf16x2_t b = __builtin_convertvector(v, bf16x2_t); return __builtin_bit_cast(unsigned, b); }
; DI void unpack8(const u32x4 w, float (&f)[8]) { f[0] = bflo(w.x); f[1] = bfhi(w.x); f[2] = bflo(w.y); f[3] = bfhi(w.y); f[4] = bflo(w.z); f[5] = bfhi(w.z); f[6] = bflo(w.w); f[7] = bfhi(w.w); }
; DI void kv_chunk(CP p, int b, int n, LAS unsigned char* lds) {
;     ...
;               unpack8(rk1, x);
; #pragma unroll
;               for (int e = 0; e < 8; ++e) *(LAS bf16*)(lds + KT + ((kpt + 8) * 8 + e) * 144 + kj * 2) = (bf16)(pk2(x[e] * w, 0.f) & 0xffffu); }
;             if (h < 3) KVR_LOAD(h + 1);
.Lkvw_r2_b:
	v_lshlrev_b32_e32 v39, 16, v12
	v_mul_f32_e32 v39, v38, v39
	v_and_b32_e32 v40, 0xffff0000, v12
	v_cvt_pk_bf16_f32 v39, v39, s0
	ds_write_b16 v36, v39 offset:18432
	v_mul_f32_e32 v39, v38, v40
	v_lshlrev_b32_e32 v41, 16, v13
	v_cvt_pk_bf16_f32 v39, v39, s0
	ds_write_b16 v49, v39 offset:27792
	v_mul_f32_e32 v39, v38, v41
	v_and_b32_e32 v42, 0xffff0000, v13
	v_cvt_pk_bf16_f32 v39, v39, s0
	ds_write_b16 v49, v39 offset:27936
	v_mul_f32_e32 v39, v38, v42
	v_lshlrev_b32_e32 v43, 16, v14
	v_cvt_pk_bf16_f32 v39, v39, s0
	ds_write_b16 v49, v39 offset:28080
	v_mul_f32_e32 v39, v38, v43
	v_and_b32_e32 v45, 0xffff0000, v14
	v_cvt_pk_bf16_f32 v39, v39, s0
	ds_write_b16 v49, v39 offset:28224
	v_mul_f32_e32 v39, v38, v45
	v_lshlrev_b32_e32 v46, 16, v15
	v_and_b32_e32 v51, 0xffff0000, v15
	v_cvt_pk_bf16_f32 v39, v39, s0
	ds_write_b16 v49, v39 offset:28368
	v_mul_f32_e32 v39, v38, v46
	v_mul_f32_e32 v38, v38, v51
	v_cvt_pk_bf16_f32 v39, v39, s0
	v_cvt_pk_bf16_f32 v38, v38, s0
	s_cmpk_eq_i32 s72, 0x300
	ds_write_b16 v49, v39 offset:28512
	ds_write_b16 v49, v38 offset:28656
	s_cbranch_scc1 .LBB0_297
	v_lshl_add_u64 v[0:1], v[26:27], 0, s[72:73]
	v_add_co_u32_e32 v2, vcc, 0xba02000, v0
	v_lshl_add_u64 v[8:9], v[24:25], 0, s[72:73]
	s_nop 0
	v_addc_co_u32_e32 v3, vcc, 0, v1, vcc
	v_add_co_u32_e32 v4, vcc, 0xba82000, v0
	s_nop 1
	v_addc_co_u32_e32 v5, vcc, 0, v1, vcc
	v_add_co_u32_e32 v12, vcc, 0xba01000, v8
	global_load_dwordx4 v[0:3], v[2:3], off offset:256
	s_nop 0
	global_load_dwordx4 v[4:7], v[4:5], off offset:256
	v_addc_co_u32_e32 v13, vcc, 0, v9, vcc
	global_load_dwordx4 v[8:11], v[12:13], off offset:3328
	s_nop 0
	global_load_dwordx4 v[12:15], v[12:13], off offset:3456
	s_branch .LBB0_297

; #define LAS __attribute__((address_space(3)))
; DI unsigned pk2(float lo, float hi) { f32x2_t v = {lo, hi}; bf16x2_t b = __builtin_convertvector(v, bf16x2_t); return __builtin_bit_cast(unsigned, b); }
; DI void unpack8(const u32x4 w, float (&f)[8]) { f[0] = bflo(w.x); f[1] = bfhi(w.x); f[2] = bflo(w.y); f[3] = bfhi(w.y); f[4] = bflo(w.z); f[5] = bfhi(w.z); f[6] = bflo(w.w); f[7] = bfhi(w.w); }
; DI void kv_chunk(CP p, int b, int n, LAS unsigned char* lds) {
;     ...
;         for (int h = 0; h < 4; ++h) {
;             *(LAS u32x4*)(lds + VT + (tid >> 4) * 272 + (tid & 15) * 16) = gv0; *(LAS u32x4*)(lds + VT + (32 + (tid >> 4)) * 272 + (tid & 15) * 16) = gv1;
;             { float x[8]; unpack8(gk, x);
;               const float wd[8] = {e0.x - c0.x, e0.y - c0.y, e0.z - c0.z, e0.w - c0.w, e1.x - c1.x, e1.y - c1.y, e1.z - c1.z, e1.w - c1.w};
; #pragma unroll
;               for (int e = 0; e < 8; ++e) *(LAS bf16*)(lds + KT + (kpt * 8 + e) * 144 + kj * 2) = (bf16)(pk2(x[e] * __expf(wd[e]), 0.f) & 0xffffu); }
.LBB0_307:
	s_cmp_eq_u32 s50, 0
	s_cbranch_scc1 .Lkvw_g1_a
	s_waitcnt vmcnt(6)
	s_branch .Lkvw_g1_b

; #define LAS __attribute__((address_space(3)))
; DI unsigned pk2(float lo, float hi) { f32x2_t v = {lo, hi}; bf16x2_t b = __builtin_convertvector(v, bf16x2_t); return __builtin_bit_cast(unsigned, b); }
; DI void unpack8(const u32x4 w, float (&f)[8]) { f[0] = bflo(w.x); f[1] = bfhi(w.x); f[2] = bflo(w.y); f[3] = bfhi(w.y); f[4] = bflo(w.z); f[5] = bfhi(w.z); f[6] = bflo(w.w); f[7] = bfhi(w.w); }
; DI void kv_chunk(CP p, int b, int n, LAS unsigned char* lds) {
;     ...
;             *(LAS u32x4*)(lds + VT + (tid >> 4) * 272 + (tid & 15) * 16) = gv0; *(LAS u32x4*)(lds + VT + (32 + (tid >> 4)) * 272 + (tid & 15) * 16) = gv1;
;             { float x[8]; unpack8(gk, x);
;               const float wd[8] = {e0.x - c0.x, e0.y - c0.y, e0.z - c0.z, e0.w - c0.w, e1.x - c1.x, e1.y - c1.y, e1.z - c1.z, e1.w - c1.w};
; #pragma unroll
;               for (int e = 0; e < 8; ++e) *(LAS bf16*)(lds + KT + (kpt * 8 + e) * 144 + kj * 2) = (bf16)(pk2(x[e] * __expf(wd[e]), 0.f) & 0xffffu); }
.Lkvw_g1_b:
	v_sub_f32_e32 v62, v16, v12
	v_mul_f32_e32 v62, 0x3fb8aa3b, v62
	v_sub_f32_e32 v63, v17, v13
	v_exp_f32_e32 v62, v62
	v_mul_f32_e32 v63, 0x3fb8aa3b, v63
	v_exp_f32_e32 v63, v63
	v_lshlrev_b32_e32 v47, 16, v8
	v_mul_f32_e32 v47, v62, v47
	v_and_b32_e32 v55, 0xffff0000, v8
	v_cvt_pk_bf16_f32 v47, v47, s0
	ds_write_b128 v48, v[0:3]
	ds_write_b128 v48, v[4:7] offset:8704
	ds_write_b16 v49, v47 offset:18432
	v_mul_f32_e32 v47, v63, v55
	v_sub_f32_e32 v143, v18, v14
	v_sub_f32_e32 v145, v19, v15
	v_cvt_pk_bf16_f32 v47, v47, s0
	v_mul_f32_e32 v55, 0x3fb8aa3b, v143
	ds_write_b16 v49, v47 offset:18576
	v_mul_f32_e32 v47, 0x3fb8aa3b, v145
	v_exp_f32_e32 v55, v55
	v_exp_f32_e32 v47, v47
	v_lshlrev_b32_e32 v56, 16, v9
	v_and_b32_e32 v57, 0xffff0000, v9
	v_mul_f32_e32 v55, v55, v56
	v_mul_f32_e32 v47, v47, v57
	s_cmp_eq_u32 s50, 0
	s_cbranch_scc1 .Lkvw_g2_a
	s_waitcnt vmcnt(4)
	s_branch .Lkvw_g2_b

; #define LAS __attribute__((address_space(3)))
; DI unsigned pk2(float lo, float hi) { f32x2_t v = {lo, hi}; bf16x2_t b = __builtin_convertvector(v, bf16x2_t); return __builtin_bit_cast(unsigned, b); }
; DI void unpack8(const u32x4 w, float (&f)[8]) { f[0] = bflo(w.x); f[1] = bfhi(w.x); f[2] = bflo(w.y); f[3] = bfhi(w.y); f[4] = bflo(w.z); f[5] = bfhi(w.z); f[6] = bflo(w.w); f[7] = bfhi(w.w); }
; DI void kv_chunk(CP p, int b, int n, LAS unsigned char* lds) {
;     ...
;             { float x[8]; unpack8(gk, x);
;               const float wd[8] = {e0.x - c0.x, e0.y - c0.y, e0.z - c0.z, e0.w - c0.w, e1.x - c1.x, e1.y - c1.y, e1.z - c1.z, e1.w - c1.w};
; #pragma unroll
;               for (int e = 0; e < 8; ++e) *(LAS bf16*)(lds + KT + (kpt * 8 + e) * 144 + kj * 2) = (bf16)(pk2(x[e] * __expf(wd[e]), 0.f) & 0xffffu); }
;             if (h < 3) KVG_LOAD(h + 1);
.Lkvw_g2_b:
	v_sub_f32_e32 v147, v24, v20
	v_sub_f32_e32 v149, v25, v21
	v_cvt_pk_bf16_f32 v55, v55, s0
	v_cvt_pk_bf16_f32 v47, v47, s0
	ds_write_b16 v49, v55 offset:18720
	v_mul_f32_e32 v55, 0x3fb8aa3b, v147
	ds_write_b16 v49, v47 offset:18864
	v_mul_f32_e32 v47, 0x3fb8aa3b, v149
	v_exp_f32_e32 v55, v55
	v_exp_f32_e32 v47, v47
	v_lshlrev_b32_e32 v58, 16, v10
	v_and_b32_e32 v59, 0xffff0000, v10
	v_mul_f32_e32 v55, v55, v58
	v_mul_f32_e32 v47, v47, v59
	v_sub_f32_e32 v151, v26, v22
	v_sub_f32_e32 v153, v27, v23
	v_cvt_pk_bf16_f32 v55, v55, s0
	v_cvt_pk_bf16_f32 v47, v47, s0
	ds_write_b16 v49, v55 offset:19008
	v_mul_f32_e32 v55, 0x3fb8aa3b, v151
	ds_write_b16 v49, v47 offset:19152
	v_mul_f32_e32 v47, 0x3fb8aa3b, v153
	v_exp_f32_e32 v55, v55
	v_exp_f32_e32 v47, v47
	v_lshlrev_b32_e32 v60, 16, v11
	v_and_b32_e32 v61, 0xffff0000, v11
	v_mul_f32_e32 v55, v55, v60
	v_mul_f32_e32 v47, v47, v61
	v_cvt_pk_bf16_f32 v55, v55, s0
	v_cvt_pk_bf16_f32 v47, v47, s0
	s_cmp_eq_u32 s50, 3
	s_mov_b32 s51, 4
	ds_write_b16 v49, v55 offset:19296
	ds_write_b16 v49, v47 offset:19440
	s_cbranch_scc1 .LBB0_306
	s_add_i32 s51, s50, 1
	s_lshl_b32 s22, s51, 8
	s_add_u32 s56, s48, s22
	s_addc_u32 s57, s49, 0
	s_lshl_b32 s22, s51, 6
	v_lshl_add_u64 v[16:17], s[22:23], 2, v[36:37]
	v_lshl_add_u64 v[0:1], v[28:29], 1, s[56:57]
	v_lshl_add_u64 v[2:3], v[30:31], 1, s[56:57]
	v_mov_b32_e32 v47, v197
	s_mov_b64 s[56:57], 0xfc00
	s_lshl_b32 s22, s51, 7
	v_lshl_add_u64 v[20:21], v[16:17], 0, v[46:47]
	v_lshl_add_u64 v[24:25], v[16:17], 0, s[56:57]
	v_add_co_u32_e32 v16, vcc, 0xf000, v16
	v_lshl_add_u64 v[0:1], v[0:1], 0, v[196:197]
	v_lshl_add_u64 v[4:5], v[2:3], 0, v[196:197]
	v_lshl_add_u64 v[8:9], v[38:39], 0, s[22:23]
	v_addc_co_u32_e32 v17, vcc, 0, v17, vcc
	global_load_dwordx4 v[0:3], v[0:1], off
	s_nop 0
	global_load_dwordx4 v[4:7], v[4:5], off
	s_nop 0
	global_load_dwordx4 v[8:11], v[8:9], off
	s_nop 0
	global_load_dwordx4 v[12:15], v[20:21], off
	s_nop 0
	global_load_dwordx4 v[16:19], v[16:17], off offset:3072
	s_nop 0
	global_load_dwordx4 v[20:23], v[20:21], off offset:16
	s_nop 0
	global_load_dwordx4 v[24:27], v[24:25], off offset:16
	s_branch .LBB0_306

; DI void phase_norm(const float* xin, const float* g, const float* shift, const float* scale, bf16* hout) {
;     ...
;     for (int row = gw; row < T; row += NGW) {
;         const int b = row >> 11;
;         const f32x4* xr = (const f32x4*)(xin + (size_t)row * DM) + lane;
;         f32x4 v[4]; float ss = 0.f;
; #pragma unroll
;         for (int j = 0; j < 4; ++j) { v[j] = xr[64 * j]; ss += (v[j].x * v[j].x + v[j].y * v[j].y) + (v[j].z * v[j].z + v[j].w * v[j].w); }
.LBB0_804:
	global_load_dwordx4 v[76:79], v[26:27], off offset:-3072
	global_load_dwordx4 v[80:83], v[26:27], off offset:-2048
	global_load_dwordx4 v[84:87], v[26:27], off offset:-1024
	global_load_dwordx4 v[88:91], v[26:27], off
	s_waitcnt vmcnt(0)
	s_branch .Lnorm_b_body

; DI int fresh_tid() { int t = threadIdx.x; asm volatile("" : "+v"(t)); return t; }
; DI unsigned pk2(float lo, float hi) { f32x2_t v = {lo, hi}; bf16x2_t b = __builtin_convertvector(v, bf16x2_t); return __builtin_bit_cast(unsigned, b); }
; DI void phase_norm(const float* xin, const float* g, const float* shift, const float* scale, bf16* hout) {
;     const int tid = fresh_tid(), lane = tid & 63, wave = tid >> 6;
;     const int gw = blockIdx.x * 8 + wave, NGW = gridDim.x * 8;
;     for (int row = gw; row < T; row += NGW) {
;         const int b = row >> 11;
;         const f32x4* xr = (const f32x4*)(xin + (size_t)row * DM) + lane;
;         f32x4 v[4]; float ss = 0.f;
; #pragma unroll
;         for (int j = 0; j < 4; ++j) { v[j] = xr[64 * j]; ss += (v[j].x * v[j].x + v[j].y * v[j].y) + (v[j].z * v[j].z + v[j].w * v[j].w); }
;         const float r = rsqrtf(wave_sum(ss, lane) * (1.f / DM) + EPS);
; #pragma unroll
;         for (int j = 0; j < 4; ++j) { const int col = 4 * lane + 256 * j;
;             const f32x4 gg = *(const f32x4*)(g + col), sc = *(const f32x4*)(scale + b * 6144 + col), sh = *(const f32x4*)(shift + b * 6144 + col);
;             const f32x4 y = (v[j] * r) * gg * (sc + 1.f) + sh;
;             u32x2 w; w.x = pk2(y.x, y.y); w.y = pk2(y.z, y.w);
;             *(u32x2*)(hout + (size_t)row * DM + col) = w; }
;     }
; }
.Lnorm_b_body:
	v_mov_b32_e32 v60, v76
	v_mov_b32_e32 v61, v77
	v_mov_b32_e32 v62, v78
	v_mov_b32_e32 v63, v79
	v_mov_b32_e32 v64, v80
	v_mov_b32_e32 v65, v81
	v_mov_b32_e32 v66, v82
	v_mov_b32_e32 v67, v83
	v_mov_b32_e32 v68, v84
	v_mov_b32_e32 v69, v85
	v_mov_b32_e32 v70, v86
	v_mov_b32_e32 v71, v87
	v_mov_b32_e32 v72, v88
	v_mov_b32_e32 v73, v89
	v_mov_b32_e32 v74, v90
	v_mov_b32_e32 v75, v91
	v_ashrrev_i32_e32 v140, 11, v16
	v_mul_i32_i24_e32 v140, 0x1800, v140
	v_ashrrev_i32_e32 v141, 31, v140
	v_lshlrev_b64 v[140:141], 2, v[140:141]
	v_lshl_add_u64 v[150:151], v[20:21], 0, v[140:141]
	v_lshl_add_u64 v[152:153], v[22:23], 0, v[140:141]
	global_load_dwordx4 v[92:95], v[18:19], off
	global_load_dwordx4 v[96:99], v[18:19], off offset:1024
	global_load_dwordx4 v[100:103], v[18:19], off offset:2048
	global_load_dwordx4 v[104:107], v[18:19], off offset:3072
	global_load_dwordx4 v[108:111], v[150:151], off
	global_load_dwordx4 v[112:115], v[150:151], off offset:1024
	global_load_dwordx4 v[116:119], v[150:151], off offset:2048
	global_load_dwordx4 v[120:123], v[150:151], off offset:3072
	global_load_dwordx4 v[124:127], v[152:153], off
	global_load_dwordx4 v[128:131], v[152:153], off offset:1024
	global_load_dwordx4 v[132:135], v[152:153], off offset:2048
	global_load_dwordx4 v[136:139], v[152:153], off offset:3072
	v_add_u32_e32 v146, s84, v16
	v_lshl_add_u64 v[148:149], v[26:27], 0, s[8:9]
	v_cmp_lt_i32_e32 vcc, s56, v146
	s_nop 1
	v_cndmask_b32_e32 v148, v148, v26, vcc
	v_cndmask_b32_e32 v149, v149, v27, vcc
	global_load_dwordx4 v[76:79], v[148:149], off offset:-3072
	global_load_dwordx4 v[80:83], v[148:149], off offset:-2048
	global_load_dwordx4 v[84:87], v[148:149], off offset:-1024
	global_load_dwordx4 v[88:91], v[148:149], off
	v_mul_f32_e32 v154, v60, v60
	v_fmac_f32_e32 v154, v61, v61
	v_mul_f32_e32 v155, v62, v62
	v_fmac_f32_e32 v155, v63, v63
	v_add_f32_e32 v154, v154, v155
	v_mov_b32_e32 v142, v154
	v_mul_f32_e32 v154, v64, v64
	v_fmac_f32_e32 v154, v65, v65
	v_mul_f32_e32 v155, v66, v66
	v_fmac_f32_e32 v155, v67, v67
	v_add_f32_e32 v154, v154, v155
	v_add_f32_e32 v142, v142, v154
	v_mul_f32_e32 v154, v68, v68
	v_fmac_f32_e32 v154, v69, v69
	v_mul_f32_e32 v155, v70, v70
	v_fmac_f32_e32 v155, v71, v71
	v_add_f32_e32 v154, v154, v155
	v_add_f32_e32 v142, v142, v154
	v_mul_f32_e32 v154, v72, v72
	v_fmac_f32_e32 v154, v73, v73
	v_mul_f32_e32 v155, v74, v74
	v_fmac_f32_e32 v155, v75, v75
	v_add_f32_e32 v154, v154, v155
	v_add_f32_e32 v142, v142, v154
	ds_bpermute_b32 v154, v29, v142
	s_waitcnt lgkmcnt(0)
	v_add_f32_e32 v142, v142, v154
	ds_bpermute_b32 v154, v34, v142
	s_waitcnt lgkmcnt(0)
	v_add_f32_e32 v142, v142, v154
	ds_bpermute_b32 v154, v35, v142
	s_waitcnt lgkmcnt(0)
	v_add_f32_e32 v142, v142, v154
	ds_bpermute_b32 v154, v36, v142
	s_waitcnt lgkmcnt(0)
	v_add_f32_e32 v142, v142, v154
	ds_bpermute_b32 v154, v37, v142
	s_waitcnt lgkmcnt(0)
	v_add_f32_e32 v142, v142, v154
	ds_bpermute_b32 v154, v38, v142
	s_waitcnt lgkmcnt(0)
	v_add_f32_e32 v142, v142, v154
	v_fmamk_f32 v142, v142, 0x3a800000, v198
	v_mul_f32_e32 v154, 0x4b800000, v142
	v_cmp_gt_f32_e32 vcc, s67, v142
	s_nop 1
	v_cndmask_b32_e32 v142, v142, v154, vcc
	v_rsq_f32_e32 v142, v142
	s_nop 0
	v_mul_f32_e32 v154, 0x45800000, v142
	v_cndmask_b32_e32 v144, v142, v154, vcc
	s_waitcnt vmcnt(4)
	v_pk_mul_f32 v[60:61], v[60:61], v[144:145] op_sel_hi:[1,0]
	v_pk_mul_f32 v[62:63], v[62:63], v[144:145] op_sel_hi:[1,0]
	v_pk_mul_f32 v[60:61], v[92:93], v[60:61]
	v_pk_mul_f32 v[62:63], v[94:95], v[62:63]
	v_pk_add_f32 v[108:109], v[108:109], 1.0 op_sel_hi:[1,0]
	v_pk_add_f32 v[110:111], v[110:111], 1.0 op_sel_hi:[1,0]
	v_pk_fma_f32 v[60:61], v[108:109], v[60:61], v[124:125]
	v_pk_fma_f32 v[62:63], v[110:111], v[62:63], v[126:127]
	v_cvt_pk_bf16_f32 v60, v60, v61
	v_cvt_pk_bf16_f32 v61, v62, v63
	global_store_dwordx2 v[24:25], v[60:61], off
	v_pk_mul_f32 v[64:65], v[64:65], v[144:145] op_sel_hi:[1,0]
	v_pk_mul_f32 v[66:67], v[66:67], v[144:145] op_sel_hi:[1,0]
	v_pk_mul_f32 v[64:65], v[96:97], v[64:65]
	v_pk_mul_f32 v[66:67], v[98:99], v[66:67]
	v_pk_add_f32 v[112:113], v[112:113], 1.0 op_sel_hi:[1,0]
	v_pk_add_f32 v[114:115], v[114:115], 1.0 op_sel_hi:[1,0]
	v_pk_fma_f32 v[64:65], v[112:113], v[64:65], v[128:129]
	v_pk_fma_f32 v[66:67], v[114:115], v[66:67], v[130:131]
	v_cvt_pk_bf16_f32 v64, v64, v65
	v_cvt_pk_bf16_f32 v65, v66, v67
	global_store_dwordx2 v[24:25], v[64:65], off offset:512
	v_pk_mul_f32 v[68:69], v[68:69], v[144:145] op_sel_hi:[1,0]
	v_pk_mul_f32 v[70:71], v[70:71], v[144:145] op_sel_hi:[1,0]
	v_pk_mul_f32 v[68:69], v[100:101], v[68:69]
	v_pk_mul_f32 v[70:71], v[102:103], v[70:71]
	v_pk_add_f32 v[116:117], v[116:117], 1.0 op_sel_hi:[1,0]
	v_pk_add_f32 v[118:119], v[118:119], 1.0 op_sel_hi:[1,0]
	v_pk_fma_f32 v[68:69], v[116:117], v[68:69], v[132:133]
	v_pk_fma_f32 v[70:71], v[118:119], v[70:71], v[134:135]
	v_cvt_pk_bf16_f32 v68, v68, v69
	v_cvt_pk_bf16_f32 v69, v70, v71
	global_store_dwordx2 v[24:25], v[68:69], off offset:1024
	v_pk_mul_f32 v[72:73], v[72:73], v[144:145] op_sel_hi:[1,0]
	v_pk_mul_f32 v[74:75], v[74:75], v[144:145] op_sel_hi:[1,0]
	v_pk_mul_f32 v[72:73], v[104:105], v[72:73]
	v_pk_mul_f32 v[74:75], v[106:107], v[74:75]
	v_pk_add_f32 v[120:121], v[120:121], 1.0 op_sel_hi:[1,0]
	v_pk_add_f32 v[122:123], v[122:123], 1.0 op_sel_hi:[1,0]
	v_pk_fma_f32 v[72:73], v[120:121], v[72:73], v[136:137]
	v_pk_fma_f32 v[74:75], v[122:123], v[74:75], v[138:139]
	v_cvt_pk_bf16_f32 v72, v72, v73
	v_cvt_pk_bf16_f32 v73, v74, v75
	global_store_dwordx2 v[24:25], v[72:73], off offset:1536
	v_mov_b32_e32 v16, v146
	v_lshl_add_u64 v[26:27], v[26:27], 0, s[8:9]
	v_cmp_lt_i32_e32 vcc, s56, v16
	s_or_b64 s[2:3], vcc, s[2:3]
	v_lshl_add_u64 v[24:25], v[24:25], 0, s[50:51]
	s_andn2_b64 exec, exec, s[2:3]
	s_cbranch_execnz .Lnorm_b_loop
